# LN2->next in-proj grid barrier replaced by row-panel barrier + wait on the LN2 panel-statistics words of the (at most 3) panels whose gu-layout R1 rows the in-proj overwrites; negative control without
# speedup vs baseline: 1.0157x; 1.0058x over previous
.LBB0_226:
	s_getreg_b32 s0, hwreg(HW_REG_XCC_ID, 0, 4)
	s_and_b32 s9, s0, 15
	s_waitcnt vmcnt(0)
	s_waitcnt vmcnt(0)
	s_barrier
	s_and_saveexec_b64 s[0:1], s[52:53]
	v_readlane_b32 s24, v255, 22
	s_cbranch_execz .LBB0_278
	v_readlane_b32 s98, v253, 2
	v_readlane_b32 s99, v253, 3
	s_nop 0
	s_add_u32 s98, s98, 0x7c000
	s_addc_u32 s99, s99, 0
	s_and_b32 vcc_hi, s2, 7
	s_sub_u32 vcc_lo, 7, vcc_hi
	s_add_u32 vcc_lo, vcc_lo, s3
	s_lshr_b32 vcc_lo, vcc_lo, 3
	s_lshl_b32 vcc_hi, vcc_hi, 8
	s_add_u32 vcc_hi, vcc_hi, 0x8000
	s_cmp_lt_u32 s101, 10
	s_cselect_b32 m0, 0, 0x800
	s_add_u32 vcc_hi, vcc_hi, m0
	v_mov_b32_e32 v3, vcc_hi
	v_mov_b32_e32 v4, 1
	s_mov_b32 vcc_hi, vcc_lo
	s_waitcnt vmcnt(0) lgkmcnt(0)
	global_atomic_add v5, v3, v4, s[98:99] sc0
	s_waitcnt vmcnt(0)
	v_readfirstlane_b32 vcc_lo, v5
	s_add_i32 vcc_lo, vcc_lo, 1
	s_cmp_ge_u32 vcc_lo, vcc_hi
	s_cbranch_scc1 .Lb3_pok_1
	s_movk_i32 m0, 0x7fff

.LBB0_292:
	s_getreg_b32 s0, hwreg(HW_REG_XCC_ID, 0, 4)
	s_and_b32 s9, s0, 15
	s_waitcnt vmcnt(0)
	v_readlane_b32 s52, v253, 4
	v_readlane_b32 s53, v253, 5
	s_barrier
	s_and_saveexec_b64 s[0:1], s[52:53]
	v_readlane_b32 s54, v255, 8
	v_readlane_b32 s55, v255, 9
	s_cbranch_execz .LBB0_344
	v_readlane_b32 s98, v253, 2
	v_readlane_b32 s99, v253, 3
	s_nop 0
	s_add_u32 s98, s98, 0x7c000
	s_addc_u32 s99, s99, 0
	s_and_b32 vcc_hi, s2, 7
	s_sub_u32 vcc_lo, 7, vcc_hi
	s_add_u32 vcc_lo, vcc_lo, s3
	s_lshr_b32 vcc_lo, vcc_lo, 3
	s_lshl_b32 vcc_hi, vcc_hi, 8
	s_add_u32 vcc_hi, vcc_hi, 0x9000
	s_cmp_lt_u32 s101, 10
	s_cselect_b32 m0, 0, 0x800
	s_add_u32 vcc_hi, vcc_hi, m0
	v_mov_b32_e32 v3, vcc_hi
	v_mov_b32_e32 v4, 1
	s_mov_b32 vcc_hi, vcc_lo
	s_waitcnt vmcnt(0) lgkmcnt(0)
	global_atomic_add v5, v3, v4, s[98:99] sc0
	v_mov_b32_e32 v6, 0xa100
	global_atomic_add v6, v4, s[98:99]
	s_waitcnt vmcnt(0)
	v_readfirstlane_b32 vcc_lo, v5
	s_add_i32 vcc_lo, vcc_lo, 1
	s_cmp_ge_u32 vcc_lo, vcc_hi
	s_cbranch_scc1 .Lb3_pok_2
	s_movk_i32 m0, 0x7fff

.Lb3_pok_7:
	s_add_i32 vcc_hi, s101, 4
	s_mul_i32 vcc_hi, vcc_hi, 13108
	s_lshr_b32 vcc_hi, vcc_hi, 16
	s_lshr_b32 vcc_hi, vcc_hi, 1
	s_mul_i32 vcc_hi, vcc_hi, s3
	v_readfirstlane_b32 vcc_lo, v7
	s_cmp_ge_u32 vcc_lo, vcc_hi
	s_cbranch_scc1 .Lb3_gok_7
	s_movk_i32 m0, 0x7fff

.Lb3_pok_9:
	s_add_i32 vcc_hi, s101, 2
	s_mul_i32 vcc_hi, vcc_hi, 13108
	s_lshr_b32 vcc_hi, vcc_hi, 16
	s_mul_i32 vcc_hi, vcc_hi, s3
	v_readfirstlane_b32 vcc_lo, v7
	s_cmp_ge_u32 vcc_lo, vcc_hi
	s_cbranch_scc1 .Lb3_gok_9
	s_movk_i32 m0, 0x7fff

.LBB0_1337:
	v_readlane_b32 s34, v255, 14
	v_readlane_b32 s22, v255, 16
	s_and_b64 vcc, exec, s[38:39]
	s_mov_b64 s[0:1], -1
	v_readlane_b32 s35, v255, 15
	v_readlane_b32 s23, v255, 17
	s_cbranch_vccnz .LBB0_1391
	s_getreg_b32 s0, hwreg(HW_REG_XCC_ID, 0, 4)
	s_and_b32 s10, s0, 15
	s_waitcnt vmcnt(0)
	s_barrier
	s_and_saveexec_b64 s[0:1], s[52:53]
	s_add_i32 s101, s101, 1
	s_cbranch_execz .LBB0_1390
	v_readlane_b32 s98, v253, 2
	v_readlane_b32 s99, v253, 3
	s_nop 0
	s_add_u32 s98, s98, 0x7c000
	s_addc_u32 s99, s99, 0
	s_and_b32 vcc_lo, s2, 63
	s_lshl_b32 vcc_lo, vcc_lo, 8
	s_add_u32 vcc_lo, vcc_lo, 0x2000
	v_mov_b32_e32 v3, vcc_lo
	v_mov_b32_e32 v4, 1
	s_lshl_b32 vcc_hi, s101, 2
	s_waitcnt vmcnt(0) lgkmcnt(0)
	global_atomic_add v5, v3, v4, s[98:99] sc0
	s_waitcnt vmcnt(0)
	v_readfirstlane_b32 vcc_lo, v5
	s_add_i32 vcc_lo, vcc_lo, 1
	s_cmp_ge_u32 vcc_lo, vcc_hi
	s_cbranch_scc1 .Lb3_pok_11
	s_movk_i32 m0, 0x7fff

.Lb3_pok_11:
	s_mul_i32 vcc_lo, s101, 13108
	s_lshr_b32 vcc_lo, vcc_lo, 16
	s_mul_i32 vcc_hi, vcc_lo, 3
	s_sub_u32 vcc_hi, vcc_hi, 1
	s_lshl_b32 vcc_hi, vcc_hi, 14
	v_readlane_b32 s98, v253, 2
	v_readlane_b32 s99, v253, 3
	s_nop 0
	s_add_u32 s98, s98, 0xc000
	s_addc_u32 s99, s99, 0
	s_add_u32 s98, s98, vcc_hi
	s_addc_u32 s99, s99, 0
	s_and_b32 vcc_lo, vcc_lo, 1
	s_cmp_eq_u32 vcc_lo, 1
	s_cselect_b32 vcc_lo, 12, 14
	s_and_b32 vcc_hi, s2, 7
	s_lshl_b32 vcc_hi, vcc_hi, 3
	s_bfe_u32 m0, s2, 0x30003
	s_add_u32 vcc_hi, vcc_hi, m0
	s_mul_i32 vcc_hi, vcc_hi, vcc_lo
	s_mul_i32 vcc_hi, vcc_hi, 5958
	s_lshr_b32 vcc_hi, vcc_hi, 16
	s_min_u32 vcc_lo, vcc_hi, 63
	s_lshl_b32 vcc_lo, vcc_lo, 8
	v_mov_b32_e32 v6, vcc_lo
	s_add_u32 vcc_hi, vcc_hi, 1
	s_min_u32 vcc_lo, vcc_hi, 63
	s_lshl_b32 vcc_lo, vcc_lo, 8
	v_mov_b32_e32 v7, vcc_lo
	s_add_u32 vcc_hi, vcc_hi, 1
	s_min_u32 vcc_lo, vcc_hi, 63
	s_lshl_b32 vcc_lo, vcc_lo, 8
	v_mov_b32_e32 v8, vcc_lo
	global_load_dword v9, v6, s[98:99] sc1
	global_load_dword v10, v7, s[98:99] sc1
	global_load_dword v11, v8, s[98:99] sc1
	s_mov_b32 vcc_hi, 32
	s_waitcnt vmcnt(0)
	v_min_u32_e32 v9, v9, v10
	v_min_u32_e32 v9, v9, v11
	s_nop 0
	v_readfirstlane_b32 vcc_lo, v9
	s_cmp_ge_u32 vcc_lo, vcc_hi
	s_cbranch_scc1 .Lb3_kok_11
	s_movk_i32 m0, 0x7fff
.Lb3_ka_11:
	global_load_dword v5, v6, s[98:99] sc1
	s_waitcnt vmcnt(0)
	v_readfirstlane_b32 vcc_lo, v5
	s_cmp_ge_u32 vcc_lo, vcc_hi
	s_cbranch_scc1 .Lb3_kaok_11
	s_sleep 1
	s_sub_u32 m0, m0, 1
	s_cmp_eq_u32 m0, 0
	s_cbranch_scc0 .Lb3_ka_11
.Lb3_kaok_11:
	s_movk_i32 m0, 0x7fff
.Lb3_kb_11:
	global_load_dword v5, v7, s[98:99] sc1
	s_waitcnt vmcnt(0)
	v_readfirstlane_b32 vcc_lo, v5
	s_cmp_ge_u32 vcc_lo, vcc_hi
	s_cbranch_scc1 .Lb3_kbok_11
	s_sleep 1
	s_sub_u32 m0, m0, 1
	s_cmp_eq_u32 m0, 0
	s_cbranch_scc0 .Lb3_kb_11

.Lb3_kc_11:
	global_load_dword v5, v8, s[98:99] sc1
	s_waitcnt vmcnt(0)
	v_readfirstlane_b32 vcc_lo, v5
	s_cmp_ge_u32 vcc_lo, vcc_hi
	s_cbranch_scc1 .Lb3_kcok_11
	s_sleep 1
	s_sub_u32 m0, m0, 1
	s_cmp_eq_u32 m0, 0
	s_cbranch_scc0 .Lb3_kc_11
.Lb3_kcok_11:
.Lb3_kok_11:
	buffer_inv sc1
	s_waitcnt vmcnt(0)
	s_branch .LBB0_1390
